# v25 plus one s_nop before P1 phase code and one before the indexer block loop (code placement only)
# speedup vs baseline: 1.0885x; 1.0070x over previous
;     __host__ __device__ bool next(int i, Unit& u) const {
;         const long L = (long)i * G + c; if (L >= nwg) return false;
;         int wgid = (int)L; { const int q = nwg / NXCD, r = nwg % NXCD, xcd = wgid % NXCD, off = wgid / NXCD; wgid = (xcd < r ? xcd * (q + 1) : r * (q + 1) + (xcd - r) * q) + off; }
;         const int nig = WGM * nN, gid = wgid / nig, fm = gid * WGM, gsz = (nM - fm) < WGM ? (nM - fm) : WGM;
;         u.pm = fm + ((wgid % nig) % gsz); u.pn = (wgid % nig) / gsz; return true;
; template <class Epi, class Sched, bool ALIGN_EPI = false, bool SP2 = false>
; __device__ __forceinline__ void gemm_phase(PG8_LAS unsigned char* lds, const Gemm g, const Sched& S, const Epi& E, const int wid  ) {
;     int lane; asm volatile("v_mbcnt_lo_u32_b32 %0, -1, 0\n\tv_mbcnt_hi_u32_b32 %0, -1, %0\n\ts_nop 1" : "=v"(lane));
;     const int tid = wid * 64 + lane, wr = wid >> 2, wc = wid & 3, fr = lane & 15, fq = lane >> 4;
.LBB0_263:
	s_or_b64 exec, exec, s[4:5]
	s_cmpk_lt_i32 s2, 0x540
	s_cselect_b64 s[4:5], -1, 0
	s_cmpk_gt_i32 s2, 0x53f
	s_waitcnt lgkmcnt(0)
	s_barrier
	v_mbcnt_lo_u32_b32 v8, -1, 0
	v_mbcnt_hi_u32_b32 v8, -1, v8
	s_nop 1
	s_cbranch_scc1 .LBB0_265
	s_ashr_i32 s0, s2, 31
	s_lshr_b32 s0, s0, 29
	s_add_i32 s0, s2, s0
	s_ashr_i32 s1, s0, 3
	s_and_b32 s0, s0, -8
	s_sub_i32 s0, s2, s0
	s_cmp_lt_i32 s0, 0
	s_movk_i32 s3, 0xa9
	s_cselect_b32 s3, s3, 0xa8
	s_mul_i32 s0, s0, s3
	s_add_i32 s0, s0, s1
	s_mul_hi_i32 s1, s0, 0x30c30c31
	s_lshr_b32 s3, s1, 31
	s_ashr_i32 s1, s1, 5
	s_add_i32 s1, s1, s3
	s_lshl_b32 s3, s1, 3
	s_mulk_i32 s1, 0xa8
	s_sub_i32 s0, s0, s1
	s_sext_i32_i16 s1, s0
	s_bfe_u32 s1, s1, 0x3001c
	s_add_i32 s1, s0, s1
	s_sext_i32_i16 s6, s1
	s_and_b32 s1, s1, 0xfff8
	s_sub_i32 s0, s0, s1
	s_sext_i32_i16 s0, s0
	s_add_i32 s24, s3, s0
	s_ashr_i32 s6, s6, 3
	s_nop 0

; __global__ void __launch_bounds__(512, 2) mega(Params p) {
;     ...
;             for (int base = 0; base < 512; base += nblk) {
;                 const int i = base + bid;
;                 if (i < 512) {
;     ...
;                     indexer_block16(Z, KI, SEL, i, lds, wave);
;                     indexer_block16(Z, KI, SEL, 1023 - i, lds, wave);
.LBB0_357:
	s_add_i32 s4, s48, s2
	s_cmpk_gt_i32 s4, 0x1ff
	s_cbranch_scc1 .LBB0_356
	s_lshl_b32 s49, s4, 4
	s_mov_b32 s98, 0
	s_nop 0

; #define LAS __attribute__((address_space(3)))
; __device__ __forceinline__ float bf_lo(unsigned v) { return __uint_as_float(v << 16); }
; __device__ __forceinline__ float bf_hi(unsigned v) { return __uint_as_float(v & 0xffff0000u); }
; __device__ __forceinline__ int lane_id() { int l; asm volatile("v_mbcnt_lo_u32_b32 %0, -1, 0\n\tv_mbcnt_hi_u32_b32 %0, -1, %0\n\ts_nop 1" : "=v"(l)); return l; }
; __device__ __forceinline__ void attn_query8(const unsigned char* __restrict__ KV8, const bf16_t* __restrict__ Z, const int* __restrict__ SEL, bf16_t* __restrict__ YMIX, int t, LAS float* sbuf  ) {
;     const int lane = lane_id(), hd = lane >> 3;
;     const int nsel = (t + 1 < 256) ? (t + 1) : 256, nb = (nsel + 7) >> 3;
;     int iv[4];
; #pragma unroll
;     for (int jj = 0; jj < 4; ++jj) { const int e = lane + 64 * jj; iv[jj] = (e < nsel) ? SEL[(size_t)t * 256 + e] : 0; }
;     f32x2v qf[8];
;     { const u32x4* qp = (const u32x4*)(Z + (size_t)t * ZLD + OFF_Q + lane * 16); const u32x4 a = qp[0], b = qp[1];
;       qf[0] = (f32x2v){bf_lo(a.x), bf_hi(a.x)}; qf[1] = (f32x2v){bf_lo(a.y), bf_hi(a.y)}; qf[2] = (f32x2v){bf_lo(a.z), bf_hi(a.z)}; qf[3] = (f32x2v){bf_lo(a.w), bf_hi(a.w)};
;       qf[4] = (f32x2v){bf_lo(b.x), bf_hi(b.x)}; qf[5] = (f32x2v){bf_lo(b.y), bf_hi(b.y)}; qf[6] = (f32x2v){bf_lo(b.z), bf_hi(b.z)}; qf[7] = (f32x2v){bf_lo(b.w), bf_hi(b.w)}; }
;     const __amdgpu_buffer_rsrc_t rs = __builtin_amdgcn_make_buffer_rsrc((void*)KV8, 0, 0x7fffffff, 0x00020000);
;     const int lvo = lane * 16;
;     LAS float* srow = sbuf + hd * 256;
.Latt_entry:
	s_mul_i32 s0, s81, 0x800
	s_and_b32 s5, s2, 7
	s_lshr_b32 s8, s2, 3
	s_lshl_b32 s8, s8, 3
	s_add_i32 s80, s8, s81
	s_lshl_b32 s8, s5, 22
	s_add_u32 s16, s60, 0x1b800000
	s_addc_u32 s17, s61, 0
	s_add_u32 s16, s16, s8
	s_addc_u32 s17, s17, 0
	s_and_b32 s17, s17, 0xffff
	s_mov_b32 s18, 0x400000
	s_mov_b32 s19, 0x20000
	s_mov_b32 s26, 0
	s_movk_i32 s27, 0x80
	s_mov_b32 s28, 0x3fb8aa3b
	v_and_b32_e32 v132, 7, v144
	v_lshlrev_b32_e32 v138, 4, v132
	v_lshrrev_b32_e32 v145, 3, v144
	v_lshl_add_u32 v139, v145, 7, s0
	v_lshl_add_u32 v148, v132, 7, s0
	v_lshl_add_u32 v148, v145, 2, v148
	v_xor_b32_e32 v140, 16, v144
	v_lshlrev_b32_e32 v140, 2, v140
	v_xor_b32_e32 v141, 32, v144
	v_lshlrev_b32_e32 v141, 2, v141
	v_mov_b32_e32 v142, 0xff800000
	v_lshlrev_b32_e32 v147, 2, v144
	s_lshl_b32 s8, s5, 8
	v_lshl_add_u32 v146, v132, 5, s8
	s_min_i32 s8, s80, 0xff
	s_add_i32 s8, s8, 1
	s_lshl_b32 s10, s80, 10
	s_add_u32 s10, s1, s10
	s_addc_u32 s11, s73, 0
	v_mov_b32_e32 v240, 0
	v_add_u32_e32 v133, 0, v144
	v_cmp_gt_i32_e32 vcc, s8, v133
	s_and_saveexec_b64 s[12:13], vcc
	global_load_dword v240, v147, s[10:11] offset:0
	s_mov_b64 exec, s[12:13]
	v_mov_b32_e32 v241, 0
	v_add_u32_e32 v133, 64, v144
	v_cmp_gt_i32_e32 vcc, s8, v133
	s_and_saveexec_b64 s[12:13], vcc
	global_load_dword v241, v147, s[10:11] offset:256
	s_mov_b64 exec, s[12:13]
	v_mov_b32_e32 v242, 0
	v_add_u32_e32 v133, 128, v144
	v_cmp_gt_i32_e32 vcc, s8, v133
	s_and_saveexec_b64 s[12:13], vcc
	global_load_dword v242, v147, s[10:11] offset:512
	s_mov_b64 exec, s[12:13]
	v_mov_b32_e32 v243, 0
	v_add_u32_e32 v133, 192, v144
	v_cmp_gt_i32_e32 vcc, s8, v133
	s_and_saveexec_b64 s[12:13], vcc
	global_load_dword v243, v147, s[10:11] offset:768
	s_mov_b64 exec, s[12:13]
	s_mul_i32 s10, s80, 0x2a00
	s_mul_hi_i32 s11, s80, 0x2a00
	s_add_u32 s10, s42, s10
	s_addc_u32 s11, s43, s11
	global_load_dwordx4 v[244:247], v146, s[10:11] offset:2048
